# v95 + counted wait (vmcnt(1) instead of vmcnt(0)) after the first store in the conv-mix loop so the store ack is not waited
# speedup vs baseline: 1.0043x; 1.0043x over previous
.LBB0_1005:
	s_waitcnt vmcnt(2)
	v_lshlrev_b32_e32 v119, 16, v56
	v_lshlrev_b32_e32 v118, 16, v48
	v_lshlrev_b32_e32 v120, 16, v72
	v_pk_mul_f32 v[118:119], v[98:99], v[118:119]
	v_lshlrev_b32_e32 v97, 16, v52
	v_fma_f32 v119, v0, v120, v119
	v_add_f32_e32 v118, v118, v119
	v_mul_f32_e32 v97, v118, v97
	v_and_b32_e32 v119, 0xffff0000, v56
	v_and_b32_e32 v118, 0xffff0000, v48
	v_and_b32_e32 v72, 0xffff0000, v72
	v_pk_mul_f32 v[118:119], v[20:21], v[118:119]
	v_lshlrev_b32_e32 v56, 16, v73
	v_fma_f32 v48, v1, v72, v119
	v_add_f32_e32 v48, v118, v48
	v_lshlrev_b32_e32 v119, 16, v57
	v_lshlrev_b32_e32 v118, 16, v49
	v_pk_mul_f32 v[118:119], v[100:101], v[118:119]
	v_and_b32_e32 v52, 0xffff0000, v52
	v_fma_f32 v56, v2, v56, v119
	v_mul_f32_e32 v48, v48, v52
	v_lshlrev_b32_e32 v52, 16, v53
	v_add_f32_e32 v56, v118, v56
	v_mul_f32_e32 v56, v56, v52
	v_and_b32_e32 v72, 0xffff0000, v53
	v_and_b32_e32 v53, 0xffff0000, v57
	v_and_b32_e32 v52, 0xffff0000, v49
	v_and_b32_e32 v73, 0xffff0000, v73
	v_pk_mul_f32 v[52:53], v[22:23], v[52:53]
	v_lshlrev_b32_e32 v57, 16, v74
	v_fma_f32 v49, v3, v73, v53
	v_add_f32_e32 v49, v52, v49
	v_lshlrev_b32_e32 v53, 16, v58
	v_lshlrev_b32_e32 v52, 16, v50
	v_pk_mul_f32 v[52:53], v[102:103], v[52:53]
	v_mul_f32_e32 v49, v49, v72
	v_fma_f32 v53, v4, v57, v53
	v_cvt_pk_bf16_f32 v48, v97, v48
	v_cvt_pk_bf16_f32 v49, v56, v49
	v_lshlrev_b32_e32 v56, 16, v54
	v_add_f32_e32 v52, v52, v53
	v_mul_f32_e32 v56, v52, v56
	v_and_b32_e32 v53, 0xffff0000, v58
	v_and_b32_e32 v52, 0xffff0000, v50
	v_and_b32_e32 v57, 0xffff0000, v74
	v_pk_mul_f32 v[52:53], v[16:17], v[52:53]
	v_and_b32_e32 v54, 0xffff0000, v54
	v_fma_f32 v50, v5, v57, v53
	v_add_f32_e32 v50, v52, v50
	v_mul_f32_e32 v50, v50, v54
	v_lshlrev_b32_e32 v53, 16, v59
	v_lshlrev_b32_e32 v52, 16, v51
	v_cvt_pk_bf16_f32 v50, v56, v50
	v_lshlrev_b32_e32 v56, 16, v75
	v_pk_mul_f32 v[52:53], v[104:105], v[52:53]
	v_lshlrev_b32_e32 v54, 16, v55
	v_fma_f32 v53, v6, v56, v53
	v_add_f32_e32 v52, v52, v53
	v_mul_f32_e32 v54, v52, v54
	v_and_b32_e32 v53, 0xffff0000, v59
	v_and_b32_e32 v52, 0xffff0000, v51
	v_and_b32_e32 v56, 0xffff0000, v75
	v_pk_mul_f32 v[52:53], v[18:19], v[52:53]
	s_add_u32 s28, s96, s40
	v_fma_f32 v51, v7, v56, v53
	v_and_b32_e32 v55, 0xffff0000, v55
	v_add_f32_e32 v51, v52, v51
	s_addc_u32 s29, s97, s41
	v_mul_f32_e32 v51, v51, v55
	v_cvt_pk_bf16_f32 v51, v54, v51
	v_lshl_add_u64 v[52:53], s[28:29], 0, v[142:143]
	global_store_dwordx4 v[52:53], v[48:51], off sc1
	s_nop 1
	s_waitcnt vmcnt(1)
	v_lshlrev_b32_e32 v49, 16, v44
	v_lshlrev_b32_e32 v48, 16, v32
	v_lshlrev_b32_e32 v51, 16, v40
	v_pk_mul_f32 v[48:49], v[106:107], v[48:49]
	v_lshlrev_b32_e32 v50, 16, v36
	v_fma_f32 v49, v8, v51, v49
	v_add_f32_e32 v48, v48, v49
	v_mul_f32_e32 v50, v48, v50
	v_and_b32_e32 v49, 0xffff0000, v44
	v_and_b32_e32 v48, 0xffff0000, v32
	v_and_b32_e32 v40, 0xffff0000, v40
	v_pk_mul_f32 v[48:49], v[28:29], v[48:49]
	v_and_b32_e32 v36, 0xffff0000, v36
	v_fma_f32 v32, v9, v40, v49
	v_add_f32_e32 v32, v48, v32
	v_lshlrev_b32_e32 v49, 16, v45
	v_lshlrev_b32_e32 v48, 16, v33
	v_lshlrev_b32_e32 v40, 16, v41
	v_pk_mul_f32 v[48:49], v[108:109], v[48:49]
	v_mul_f32_e32 v32, v32, v36
	v_fma_f32 v40, v10, v40, v49
	v_lshlrev_b32_e32 v36, 16, v37
	v_add_f32_e32 v40, v48, v40
	v_mul_f32_e32 v40, v40, v36
	v_and_b32_e32 v44, 0xffff0000, v37
	v_and_b32_e32 v37, 0xffff0000, v45
	v_and_b32_e32 v36, 0xffff0000, v33
	v_and_b32_e32 v41, 0xffff0000, v41
	v_pk_mul_f32 v[36:37], v[30:31], v[36:37]
	v_cvt_pk_bf16_f32 v32, v50, v32
	s_and_b64 vcc, exec, s[38:39]
	v_fma_f32 v33, v11, v41, v37
	v_add_f32_e32 v33, v36, v33
	v_lshlrev_b32_e32 v37, 16, v46
	v_lshlrev_b32_e32 v36, 16, v34
	v_lshlrev_b32_e32 v41, 16, v42
	v_pk_mul_f32 v[36:37], v[110:111], v[36:37]
	v_mul_f32_e32 v33, v33, v44
	v_fma_f32 v37, v12, v41, v37
	v_cvt_pk_bf16_f32 v33, v40, v33
	v_lshlrev_b32_e32 v40, 16, v38
	v_add_f32_e32 v36, v36, v37
	v_mul_f32_e32 v40, v36, v40
	v_and_b32_e32 v37, 0xffff0000, v46
	v_and_b32_e32 v36, 0xffff0000, v34
	v_and_b32_e32 v41, 0xffff0000, v42
	v_pk_mul_f32 v[36:37], v[24:25], v[36:37]
	v_and_b32_e32 v38, 0xffff0000, v38
	v_fma_f32 v34, v13, v41, v37
	v_add_f32_e32 v34, v36, v34
	v_mul_f32_e32 v34, v34, v38
	v_lshlrev_b32_e32 v37, 16, v47
	v_lshlrev_b32_e32 v36, 16, v35
	v_cvt_pk_bf16_f32 v34, v40, v34
	v_lshlrev_b32_e32 v40, 16, v43
	v_pk_mul_f32 v[36:37], v[112:113], v[36:37]
	v_lshlrev_b32_e32 v38, 16, v39
	v_fma_f32 v37, v14, v40, v37
	v_add_f32_e32 v36, v36, v37
	v_mul_f32_e32 v38, v36, v38
	v_and_b32_e32 v37, 0xffff0000, v47
	v_and_b32_e32 v36, 0xffff0000, v35
	v_and_b32_e32 v40, 0xffff0000, v43
	v_pk_mul_f32 v[36:37], v[26:27], v[36:37]
	v_and_b32_e32 v39, 0xffff0000, v39
	v_fma_f32 v35, v15, v40, v37
	v_add_f32_e32 v35, v36, v35
	v_mul_f32_e32 v35, v35, v39
	v_cvt_pk_bf16_f32 v35, v38, v35
	v_lshl_add_u64 v[36:37], v[52:53], 0, s[10:11]
	global_store_dwordx4 v[36:37], v[32:35], off sc1
	s_nop 1
	s_cbranch_vccnz .LBB0_961
	v_lshlrev_b32_e32 v33, 16, v84
	v_lshlrev_b32_e32 v32, 16, v64
	v_lshlrev_b32_e32 v35, 16, v92
	v_pk_mul_f32 v[32:33], v[98:99], v[32:33]
	v_lshlrev_b32_e32 v34, 16, v60
	v_fma_f32 v33, v0, v35, v33
	v_add_f32_e32 v32, v32, v33
	v_mul_f32_e32 v34, v32, v34
	v_and_b32_e32 v33, 0xffff0000, v84
	v_and_b32_e32 v32, 0xffff0000, v64
	v_and_b32_e32 v36, 0xffff0000, v92
	v_pk_mul_f32 v[32:33], v[20:21], v[32:33]
	v_and_b32_e32 v35, 0xffff0000, v60
	v_fma_f32 v33, v1, v36, v33
	v_add_f32_e32 v32, v32, v33
	v_mul_f32_e32 v32, v32, v35
	v_cvt_pk_bf16_f32 v32, v34, v32
	v_lshlrev_b32_e32 v34, 16, v65
	v_lshlrev_b32_e32 v35, 16, v85
	v_lshlrev_b32_e32 v36, 16, v93
	v_pk_mul_f32 v[34:35], v[100:101], v[34:35]
	v_lshlrev_b32_e32 v33, 16, v61
	v_fma_f32 v35, v2, v36, v35
	v_add_f32_e32 v34, v34, v35
	v_mul_f32_e32 v33, v34, v33
	v_and_b32_e32 v35, 0xffff0000, v85
	v_and_b32_e32 v34, 0xffff0000, v65
	v_and_b32_e32 v37, 0xffff0000, v93
	v_pk_mul_f32 v[34:35], v[22:23], v[34:35]
	v_and_b32_e32 v36, 0xffff0000, v61
	v_fma_f32 v35, v3, v37, v35
	v_add_f32_e32 v34, v34, v35
	v_mul_f32_e32 v34, v34, v36
	v_cvt_pk_bf16_f32 v33, v33, v34
	v_lshlrev_b32_e32 v35, 16, v86
	v_lshlrev_b32_e32 v34, 16, v66
	v_lshlrev_b32_e32 v37, 16, v94
	v_pk_mul_f32 v[34:35], v[102:103], v[34:35]
	v_lshlrev_b32_e32 v36, 16, v62
	v_fma_f32 v35, v4, v37, v35
	v_add_f32_e32 v34, v34, v35
	v_mul_f32_e32 v36, v34, v36
	v_and_b32_e32 v35, 0xffff0000, v86
	v_and_b32_e32 v34, 0xffff0000, v66
	v_and_b32_e32 v38, 0xffff0000, v94
	v_pk_mul_f32 v[34:35], v[16:17], v[34:35]
	v_and_b32_e32 v37, 0xffff0000, v62
	v_fma_f32 v35, v5, v38, v35
	v_add_f32_e32 v34, v34, v35
	v_mul_f32_e32 v34, v34, v37
	v_cvt_pk_bf16_f32 v34, v36, v34
	v_lshlrev_b32_e32 v36, 16, v67
	v_lshlrev_b32_e32 v37, 16, v87
	v_lshlrev_b32_e32 v38, 16, v95
	v_pk_mul_f32 v[36:37], v[104:105], v[36:37]
	v_lshlrev_b32_e32 v35, 16, v63
	v_fma_f32 v37, v6, v38, v37
	v_add_f32_e32 v36, v36, v37
	v_mul_f32_e32 v35, v36, v35
	v_and_b32_e32 v37, 0xffff0000, v87
	v_and_b32_e32 v36, 0xffff0000, v67
	v_and_b32_e32 v39, 0xffff0000, v95
	v_pk_mul_f32 v[36:37], v[18:19], v[36:37]
	s_add_u32 s28, s96, s42
	v_fma_f32 v37, v7, v39, v37
	v_and_b32_e32 v38, 0xffff0000, v63
	v_add_f32_e32 v36, v36, v37
	s_addc_u32 s29, s97, s43
	v_mul_f32_e32 v36, v36, v38
	v_cvt_pk_bf16_f32 v35, v35, v36
	v_lshl_add_u64 v[36:37], s[28:29], 0, v[142:143]
	global_store_dwordx4 v[36:37], v[32:35], off sc1
	s_nop 1
	v_lshlrev_b32_e32 v33, 16, v68
	v_lshlrev_b32_e32 v32, 16, v80
	v_lshlrev_b32_e32 v35, 16, v88
	v_pk_mul_f32 v[32:33], v[106:107], v[32:33]
	v_lshlrev_b32_e32 v34, 16, v76
	v_fma_f32 v33, v8, v35, v33
	v_add_f32_e32 v32, v32, v33
	v_mul_f32_e32 v34, v32, v34
	v_and_b32_e32 v33, 0xffff0000, v68
	v_and_b32_e32 v32, 0xffff0000, v80
	v_and_b32_e32 v38, 0xffff0000, v88
	v_pk_mul_f32 v[32:33], v[28:29], v[32:33]
	v_and_b32_e32 v35, 0xffff0000, v76
	v_fma_f32 v33, v9, v38, v33
	v_add_f32_e32 v32, v32, v33
	v_mul_f32_e32 v32, v32, v35
	v_cvt_pk_bf16_f32 v32, v34, v32
	v_lshlrev_b32_e32 v34, 16, v81
	v_lshlrev_b32_e32 v35, 16, v69
	v_lshlrev_b32_e32 v38, 16, v89
	v_pk_mul_f32 v[34:35], v[108:109], v[34:35]
	v_lshlrev_b32_e32 v33, 16, v77
	v_fma_f32 v35, v10, v38, v35
	v_add_f32_e32 v34, v34, v35
	v_mul_f32_e32 v33, v34, v33
	v_and_b32_e32 v35, 0xffff0000, v69
	v_and_b32_e32 v34, 0xffff0000, v81
	v_and_b32_e32 v39, 0xffff0000, v89
	v_pk_mul_f32 v[34:35], v[30:31], v[34:35]
	v_and_b32_e32 v38, 0xffff0000, v77
	v_fma_f32 v35, v11, v39, v35
	v_add_f32_e32 v34, v34, v35
	v_mul_f32_e32 v34, v34, v38
	v_cvt_pk_bf16_f32 v33, v33, v34
	v_lshlrev_b32_e32 v35, 16, v70
	v_lshlrev_b32_e32 v34, 16, v82
	v_lshlrev_b32_e32 v39, 16, v90
	v_pk_mul_f32 v[34:35], v[110:111], v[34:35]
	v_lshlrev_b32_e32 v38, 16, v78
	v_fma_f32 v35, v12, v39, v35
	v_add_f32_e32 v34, v34, v35
	v_mul_f32_e32 v38, v34, v38
	v_and_b32_e32 v35, 0xffff0000, v70
	v_and_b32_e32 v34, 0xffff0000, v82
	v_and_b32_e32 v40, 0xffff0000, v90
	v_pk_mul_f32 v[34:35], v[24:25], v[34:35]
	v_and_b32_e32 v39, 0xffff0000, v78
	v_fma_f32 v35, v13, v40, v35
	v_add_f32_e32 v34, v34, v35
	v_mul_f32_e32 v34, v34, v39
	v_cvt_pk_bf16_f32 v34, v38, v34
	v_lshlrev_b32_e32 v38, 16, v83
	v_lshlrev_b32_e32 v39, 16, v71
	v_lshlrev_b32_e32 v40, 16, v91
	v_pk_mul_f32 v[38:39], v[112:113], v[38:39]
	v_lshlrev_b32_e32 v35, 16, v79
	v_fma_f32 v39, v14, v40, v39
	v_add_f32_e32 v38, v38, v39
	v_mul_f32_e32 v35, v38, v35
	v_and_b32_e32 v39, 0xffff0000, v71
	v_and_b32_e32 v38, 0xffff0000, v83
	v_and_b32_e32 v41, 0xffff0000, v91
	v_pk_mul_f32 v[38:39], v[26:27], v[38:39]
	v_and_b32_e32 v40, 0xffff0000, v79
	v_fma_f32 v39, v15, v41, v39
	v_add_f32_e32 v38, v38, v39
	v_mul_f32_e32 v38, v38, v40
	v_cvt_pk_bf16_f32 v35, v35, v38
	v_lshl_add_u64 v[36:37], v[36:37], 0, s[10:11]
	global_store_dwordx4 v[36:37], v[32:35], off sc1
	s_nop 1
	s_branch .LBB0_961
